# phase +6 epilogue silu(gate)*up batched with packed ops (removes dependency-chain hazard nops); stacked on v26
# baseline (speedup 1.0000x reference)
; __device__ __forceinline__ unsigned pk2(float lo, float hi) { unsigned r; asm volatile("v_cvt_pk_bf16_f32 %0, %1, %2" : "=v"(r) : "v"(lo), "v"(hi)); return r; }
;     __device__ __forceinline__ void operator()(const f32x4 (&acc)[2][2][4][2], const Unit& u, int wr, int wc, int fr, int fq) const { if (u.sel == 0) e0(acc, u, wr, wc, fr, fq); else e1(acc, u, wr, wc, fr, fq); }
; __device__ __forceinline__ float sigmoid_fast(float x) { return __builtin_amdgcn_rcpf(1.0f + __expf(-x)); }
;     __device__ __forceinline__ void operator()(const f32x4 (&acc)[2][2][4][2], const Unit& u, int wr, int wc, int fr, int fq) const {
;         const int col0 = u.pn * 128 + wc * 32 + 8 * fq;
; #pragma unroll
;         for (int ai = 0; ai < 2; ++ai)
; #pragma unroll
;             for (int m = 0; m < 4; ++m) {
;                 bf16* rowp = H + ((size_t)u.pm * 256 + ai * 128 + wr * 64 + m * 16 + fr) * 512 + col0;
;                 float h[8];
; #pragma unroll
;                 for (int n = 0; n < 2; ++n)
; #pragma unroll
;                     for (int j = 0; j < 4; ++j) { const float g = acc[ai][0][m][n][j], up = acc[ai][1][m][n][j]; h[n * 4 + j] = g * sigmoid_fast(g) * up; }
;                 u32x4 w; w.x = pk2(h[0], h[1]); w.y = pk2(h[2], h[3]); w.z = pk2(h[4], h[5]); w.w = pk2(h[6], h[7]);
;                 *(u32x4*)rowp = w;
;             }
.LBB0_1320:
	v_lshl_or_b32 v132, s35, 7, v243
	s_ashr_i32 s35, s34, 31
	s_lshl_b64 s[34:35], s[34:35], 18
	v_ashrrev_i32_e32 v133, 31, v132
	v_lshl_add_u64 v[134:135], v[214:215], 0, s[34:35]
	v_lshl_add_u64 v[136:137], v[132:133], 1, v[134:135]
	s_mov_b32 s36, 0xbfb8aa3b
	s_mov_b32 s37, 0xbfb8aa3b
	s_mov_b32 s40, 1.0
	s_mov_b32 s41, 1.0
	s_mov_b32 s35, 0
	v_pk_mul_f32 v[140:141], v[124:125], s[36:37]
	v_pk_mul_f32 v[142:143], v[126:127], s[36:37]
	v_pk_mul_f32 v[144:145], v[120:121], s[36:37]
	v_pk_mul_f32 v[146:147], v[122:123], s[36:37]
	v_exp_f32_e32 v140, v140
	v_exp_f32_e32 v141, v141
	v_exp_f32_e32 v142, v142
	v_exp_f32_e32 v143, v143
	v_exp_f32_e32 v144, v144
	v_exp_f32_e32 v145, v145
	v_exp_f32_e32 v146, v146
	v_exp_f32_e32 v147, v147
	v_pk_add_f32 v[140:141], v[140:141], s[40:41]
	v_pk_add_f32 v[142:143], v[142:143], s[40:41]
	v_pk_add_f32 v[144:145], v[144:145], s[40:41]
	v_pk_add_f32 v[146:147], v[146:147], s[40:41]
	v_rcp_f32_e32 v140, v140
	v_rcp_f32_e32 v141, v141
	v_rcp_f32_e32 v142, v142
	v_rcp_f32_e32 v143, v143
	v_rcp_f32_e32 v144, v144
	v_rcp_f32_e32 v145, v145
	v_rcp_f32_e32 v146, v146
	v_rcp_f32_e32 v147, v147
	v_pk_mul_f32 v[124:125], v[124:125], v[140:141]
	v_pk_mul_f32 v[126:127], v[126:127], v[142:143]
	v_pk_mul_f32 v[120:121], v[120:121], v[144:145]
	v_pk_mul_f32 v[122:123], v[122:123], v[146:147]
	v_pk_mul_f32 v[124:125], v[128:129], v[124:125]
	v_pk_mul_f32 v[126:127], v[130:131], v[126:127]
	v_pk_mul_f32 v[120:121], v[116:117], v[120:121]
	v_pk_mul_f32 v[122:123], v[118:119], v[122:123]
	v_cvt_pk_bf16_f32 v124, v124, v125
	v_cvt_pk_bf16_f32 v125, v126, v127
	v_cvt_pk_bf16_f32 v126, v120, v121
	v_cvt_pk_bf16_f32 v127, v122, v123
	global_store_dwordx4 v[136:137], v[124:127], off
	v_pk_mul_f32 v[140:141], v[112:113], s[36:37]
	v_pk_mul_f32 v[142:143], v[114:115], s[36:37]
	v_pk_mul_f32 v[144:145], v[104:105], s[36:37]
	v_pk_mul_f32 v[146:147], v[106:107], s[36:37]
	v_exp_f32_e32 v140, v140
	v_exp_f32_e32 v141, v141
	v_exp_f32_e32 v142, v142
	v_exp_f32_e32 v143, v143
	v_exp_f32_e32 v144, v144
	v_exp_f32_e32 v145, v145
	v_exp_f32_e32 v146, v146
	v_exp_f32_e32 v147, v147
	v_pk_add_f32 v[140:141], v[140:141], s[40:41]
	v_pk_add_f32 v[142:143], v[142:143], s[40:41]
	v_pk_add_f32 v[144:145], v[144:145], s[40:41]
	v_pk_add_f32 v[146:147], v[146:147], s[40:41]
	v_rcp_f32_e32 v140, v140
	v_rcp_f32_e32 v141, v141
	v_rcp_f32_e32 v142, v142
	v_rcp_f32_e32 v143, v143
	v_rcp_f32_e32 v144, v144
	v_rcp_f32_e32 v145, v145
	v_rcp_f32_e32 v146, v146
	v_rcp_f32_e32 v147, v147
	v_pk_mul_f32 v[112:113], v[112:113], v[140:141]
	v_pk_mul_f32 v[114:115], v[114:115], v[142:143]
	v_pk_mul_f32 v[104:105], v[104:105], v[144:145]
	v_pk_mul_f32 v[106:107], v[106:107], v[146:147]
	v_pk_mul_f32 v[112:113], v[108:109], v[112:113]
	v_pk_mul_f32 v[114:115], v[110:111], v[114:115]
	v_pk_mul_f32 v[104:105], v[100:101], v[104:105]
	v_pk_mul_f32 v[106:107], v[102:103], v[106:107]
	v_cvt_pk_bf16_f32 v112, v112, v113
	v_cvt_pk_bf16_f32 v113, v114, v115
	v_cvt_pk_bf16_f32 v114, v104, v105
	v_cvt_pk_bf16_f32 v115, v106, v107
	s_mov_b32 s34, 0x4000
	v_lshl_add_u64 v[138:139], v[136:137], 0, s[34:35]
	global_store_dwordx4 v[138:139], v[112:115], off
	v_pk_mul_f32 v[140:141], v[96:97], s[36:37]
	v_pk_mul_f32 v[142:143], v[98:99], s[36:37]
	v_pk_mul_f32 v[144:145], v[88:89], s[36:37]
	v_pk_mul_f32 v[146:147], v[90:91], s[36:37]
	v_exp_f32_e32 v140, v140
	v_exp_f32_e32 v141, v141
	v_exp_f32_e32 v142, v142
	v_exp_f32_e32 v143, v143
	v_exp_f32_e32 v144, v144
	v_exp_f32_e32 v145, v145
	v_exp_f32_e32 v146, v146
	v_exp_f32_e32 v147, v147
	v_pk_add_f32 v[140:141], v[140:141], s[40:41]
	v_pk_add_f32 v[142:143], v[142:143], s[40:41]
	v_pk_add_f32 v[144:145], v[144:145], s[40:41]
	v_pk_add_f32 v[146:147], v[146:147], s[40:41]
	v_rcp_f32_e32 v140, v140
	v_rcp_f32_e32 v141, v141
	v_rcp_f32_e32 v142, v142
	v_rcp_f32_e32 v143, v143
	v_rcp_f32_e32 v144, v144
	v_rcp_f32_e32 v145, v145
	v_rcp_f32_e32 v146, v146
	v_rcp_f32_e32 v147, v147
	v_pk_mul_f32 v[96:97], v[96:97], v[140:141]
	v_pk_mul_f32 v[98:99], v[98:99], v[142:143]
	v_pk_mul_f32 v[88:89], v[88:89], v[144:145]
	v_pk_mul_f32 v[90:91], v[90:91], v[146:147]
	v_pk_mul_f32 v[96:97], v[92:93], v[96:97]
	v_pk_mul_f32 v[98:99], v[94:95], v[98:99]
	v_pk_mul_f32 v[88:89], v[84:85], v[88:89]
	v_pk_mul_f32 v[90:91], v[86:87], v[90:91]
	v_cvt_pk_bf16_f32 v96, v96, v97
	v_cvt_pk_bf16_f32 v97, v98, v99
	v_cvt_pk_bf16_f32 v98, v88, v89
	v_cvt_pk_bf16_f32 v99, v90, v91
	s_mov_b32 s34, 0x8000
	v_lshl_add_u64 v[138:139], v[136:137], 0, s[34:35]
	global_store_dwordx4 v[138:139], v[96:99], off
	v_pk_mul_f32 v[140:141], v[80:81], s[36:37]
	v_pk_mul_f32 v[142:143], v[82:83], s[36:37]
	v_pk_mul_f32 v[144:145], v[72:73], s[36:37]
	v_pk_mul_f32 v[146:147], v[74:75], s[36:37]
	v_exp_f32_e32 v140, v140
	v_exp_f32_e32 v141, v141
	v_exp_f32_e32 v142, v142
	v_exp_f32_e32 v143, v143
	v_exp_f32_e32 v144, v144
	v_exp_f32_e32 v145, v145
	v_exp_f32_e32 v146, v146
	v_exp_f32_e32 v147, v147
	v_pk_add_f32 v[140:141], v[140:141], s[40:41]
	v_pk_add_f32 v[142:143], v[142:143], s[40:41]
	v_pk_add_f32 v[144:145], v[144:145], s[40:41]
	v_pk_add_f32 v[146:147], v[146:147], s[40:41]
	v_rcp_f32_e32 v140, v140
	v_rcp_f32_e32 v141, v141
	v_rcp_f32_e32 v142, v142
	v_rcp_f32_e32 v143, v143
	v_rcp_f32_e32 v144, v144
	v_rcp_f32_e32 v145, v145
	v_rcp_f32_e32 v146, v146
	v_rcp_f32_e32 v147, v147
	v_pk_mul_f32 v[80:81], v[80:81], v[140:141]
	v_pk_mul_f32 v[82:83], v[82:83], v[142:143]
	v_pk_mul_f32 v[72:73], v[72:73], v[144:145]
	v_pk_mul_f32 v[74:75], v[74:75], v[146:147]
	v_pk_mul_f32 v[80:81], v[76:77], v[80:81]
	v_pk_mul_f32 v[82:83], v[78:79], v[82:83]
; __device__ __forceinline__ unsigned pk2(float lo, float hi) { unsigned r; asm volatile("v_cvt_pk_bf16_f32 %0, %1, %2" : "=v"(r) : "v"(lo), "v"(hi)); return r; }
; __device__ __forceinline__ float sigmoid_fast(float x) { return __builtin_amdgcn_rcpf(1.0f + __expf(-x)); }
;     __device__ __forceinline__ void operator()(const f32x4 (&acc)[2][2][4][2], const Unit& u, int wr, int wc, int fr, int fq) const { if (u.sel == 0) e0(acc, u, wr, wc, fr, fq); else e1(acc, u, wr, wc, fr, fq); }
;     __device__ __forceinline__ void operator()(const f32x4 (&acc)[2][2][4][2], const Unit& u, int wr, int wc, int fr, int fq) const {
;         const int col0 = u.pn * 128 + wc * 32 + 8 * fq;
; #pragma unroll
;         for (int ai = 0; ai < 2; ++ai)
; #pragma unroll
;             for (int m = 0; m < 4; ++m) {
;                 bf16* rowp = H + ((size_t)u.pm * 256 + ai * 128 + wr * 64 + m * 16 + fr) * 512 + col0;
;                 float h[8];
; #pragma unroll
;                 for (int n = 0; n < 2; ++n)
; #pragma unroll
;                     for (int j = 0; j < 4; ++j) { const float g = acc[ai][0][m][n][j], up = acc[ai][1][m][n][j]; h[n * 4 + j] = g * sigmoid_fast(g) * up; }
;                 u32x4 w; w.x = pk2(h[0], h[1]); w.y = pk2(h[2], h[3]); w.z = pk2(h[4], h[5]); w.w = pk2(h[6], h[7]);
;                 *(u32x4*)rowp = w;
;             }
;     }
	v_pk_mul_f32 v[72:73], v[68:69], v[72:73]
	v_pk_mul_f32 v[74:75], v[70:71], v[74:75]
	v_cvt_pk_bf16_f32 v80, v80, v81
	v_cvt_pk_bf16_f32 v81, v82, v83
	v_cvt_pk_bf16_f32 v82, v72, v73
	v_cvt_pk_bf16_f32 v83, v74, v75
	s_mov_b32 s34, 0xc000
	v_lshl_add_u64 v[138:139], v[136:137], 0, s[34:35]
	global_store_dwordx4 v[138:139], v[80:83], off
	v_pk_mul_f32 v[140:141], v[64:65], s[36:37]
	v_pk_mul_f32 v[142:143], v[66:67], s[36:37]
	v_pk_mul_f32 v[144:145], v[56:57], s[36:37]
	v_pk_mul_f32 v[146:147], v[58:59], s[36:37]
	v_exp_f32_e32 v140, v140
	v_exp_f32_e32 v141, v141
	v_exp_f32_e32 v142, v142
	v_exp_f32_e32 v143, v143
	v_exp_f32_e32 v144, v144
	v_exp_f32_e32 v145, v145
	v_exp_f32_e32 v146, v146
	v_exp_f32_e32 v147, v147
	v_pk_add_f32 v[140:141], v[140:141], s[40:41]
	v_pk_add_f32 v[142:143], v[142:143], s[40:41]
	v_pk_add_f32 v[144:145], v[144:145], s[40:41]
	v_pk_add_f32 v[146:147], v[146:147], s[40:41]
	v_rcp_f32_e32 v140, v140
	v_rcp_f32_e32 v141, v141
	v_rcp_f32_e32 v142, v142
	v_rcp_f32_e32 v143, v143
	v_rcp_f32_e32 v144, v144
	v_rcp_f32_e32 v145, v145
	v_rcp_f32_e32 v146, v146
	v_rcp_f32_e32 v147, v147
	v_pk_mul_f32 v[64:65], v[64:65], v[140:141]
	v_pk_mul_f32 v[66:67], v[66:67], v[142:143]
	v_pk_mul_f32 v[56:57], v[56:57], v[144:145]
	v_pk_mul_f32 v[58:59], v[58:59], v[146:147]
	v_pk_mul_f32 v[64:65], v[60:61], v[64:65]
	v_pk_mul_f32 v[66:67], v[62:63], v[66:67]
	v_pk_mul_f32 v[56:57], v[52:53], v[56:57]
	v_pk_mul_f32 v[58:59], v[54:55], v[58:59]
	v_cvt_pk_bf16_f32 v64, v64, v65
	v_cvt_pk_bf16_f32 v65, v66, v67
	v_cvt_pk_bf16_f32 v66, v56, v57
	v_cvt_pk_bf16_f32 v67, v58, v59
	s_mov_b32 s34, 0x20000
	v_lshl_add_u64 v[138:139], v[136:137], 0, s[34:35]
	global_store_dwordx4 v[138:139], v[64:67], off
	v_pk_mul_f32 v[140:141], v[48:49], s[36:37]
	v_pk_mul_f32 v[142:143], v[50:51], s[36:37]
	v_pk_mul_f32 v[144:145], v[40:41], s[36:37]
	v_pk_mul_f32 v[146:147], v[42:43], s[36:37]
	v_exp_f32_e32 v140, v140
	v_exp_f32_e32 v141, v141
	v_exp_f32_e32 v142, v142
	v_exp_f32_e32 v143, v143
	v_exp_f32_e32 v144, v144
	v_exp_f32_e32 v145, v145
	v_exp_f32_e32 v146, v146
	v_exp_f32_e32 v147, v147
	v_pk_add_f32 v[140:141], v[140:141], s[40:41]
	v_pk_add_f32 v[142:143], v[142:143], s[40:41]
	v_pk_add_f32 v[144:145], v[144:145], s[40:41]
	v_pk_add_f32 v[146:147], v[146:147], s[40:41]
	v_rcp_f32_e32 v140, v140
	v_rcp_f32_e32 v141, v141
	v_rcp_f32_e32 v142, v142
	v_rcp_f32_e32 v143, v143
	v_rcp_f32_e32 v144, v144
	v_rcp_f32_e32 v145, v145
	v_rcp_f32_e32 v146, v146
	v_rcp_f32_e32 v147, v147
	v_pk_mul_f32 v[48:49], v[48:49], v[140:141]
	v_pk_mul_f32 v[50:51], v[50:51], v[142:143]
	v_pk_mul_f32 v[40:41], v[40:41], v[144:145]
	v_pk_mul_f32 v[42:43], v[42:43], v[146:147]
	v_pk_mul_f32 v[48:49], v[44:45], v[48:49]
	v_pk_mul_f32 v[50:51], v[46:47], v[50:51]
	v_pk_mul_f32 v[40:41], v[36:37], v[40:41]
	v_pk_mul_f32 v[42:43], v[38:39], v[42:43]
	v_cvt_pk_bf16_f32 v48, v48, v49
	v_cvt_pk_bf16_f32 v49, v50, v51
	v_cvt_pk_bf16_f32 v50, v40, v41
	v_cvt_pk_bf16_f32 v51, v42, v43
	s_mov_b32 s34, 0x24000
	v_lshl_add_u64 v[138:139], v[136:137], 0, s[34:35]
	global_store_dwordx4 v[138:139], v[48:51], off
	v_pk_mul_f32 v[140:141], v[32:33], s[36:37]
	v_pk_mul_f32 v[142:143], v[34:35], s[36:37]
	v_pk_mul_f32 v[144:145], v[24:25], s[36:37]
	v_pk_mul_f32 v[146:147], v[26:27], s[36:37]
	v_exp_f32_e32 v140, v140
	v_exp_f32_e32 v141, v141
	v_exp_f32_e32 v142, v142
	v_exp_f32_e32 v143, v143
	v_exp_f32_e32 v144, v144
	v_exp_f32_e32 v145, v145
	v_exp_f32_e32 v146, v146
	v_exp_f32_e32 v147, v147
	v_pk_add_f32 v[140:141], v[140:141], s[40:41]
	v_pk_add_f32 v[142:143], v[142:143], s[40:41]
	v_pk_add_f32 v[144:145], v[144:145], s[40:41]
	v_pk_add_f32 v[146:147], v[146:147], s[40:41]
	v_rcp_f32_e32 v140, v140
	v_rcp_f32_e32 v141, v141
	v_rcp_f32_e32 v142, v142
	v_rcp_f32_e32 v143, v143
	v_rcp_f32_e32 v144, v144
	v_rcp_f32_e32 v145, v145
	v_rcp_f32_e32 v146, v146
	v_rcp_f32_e32 v147, v147
	v_pk_mul_f32 v[32:33], v[32:33], v[140:141]
	v_pk_mul_f32 v[34:35], v[34:35], v[142:143]
	v_pk_mul_f32 v[24:25], v[24:25], v[144:145]
	v_pk_mul_f32 v[26:27], v[26:27], v[146:147]
	v_pk_mul_f32 v[32:33], v[28:29], v[32:33]
	v_pk_mul_f32 v[34:35], v[30:31], v[34:35]
	v_pk_mul_f32 v[24:25], v[20:21], v[24:25]
	v_pk_mul_f32 v[26:27], v[22:23], v[26:27]
	v_cvt_pk_bf16_f32 v32, v32, v33
	v_cvt_pk_bf16_f32 v33, v34, v35
	v_cvt_pk_bf16_f32 v34, v24, v25
	v_cvt_pk_bf16_f32 v35, v26, v27
	s_mov_b32 s34, 0x28000
	v_lshl_add_u64 v[138:139], v[136:137], 0, s[34:35]
	global_store_dwordx4 v[138:139], v[32:35], off
	v_pk_mul_f32 v[140:141], v[16:17], s[36:37]
	v_pk_mul_f32 v[142:143], v[18:19], s[36:37]
	v_pk_mul_f32 v[144:145], v[8:9], s[36:37]
	v_pk_mul_f32 v[146:147], v[10:11], s[36:37]
	v_exp_f32_e32 v140, v140
	v_exp_f32_e32 v141, v141
	v_exp_f32_e32 v142, v142
	v_exp_f32_e32 v143, v143
	v_exp_f32_e32 v144, v144
	v_exp_f32_e32 v145, v145
	v_exp_f32_e32 v146, v146
	v_exp_f32_e32 v147, v147
	v_pk_add_f32 v[140:141], v[140:141], s[40:41]
	v_pk_add_f32 v[142:143], v[142:143], s[40:41]
	v_pk_add_f32 v[144:145], v[144:145], s[40:41]
	v_pk_add_f32 v[146:147], v[146:147], s[40:41]
	v_rcp_f32_e32 v140, v140
	v_rcp_f32_e32 v141, v141
	v_rcp_f32_e32 v142, v142
	v_rcp_f32_e32 v143, v143
	v_rcp_f32_e32 v144, v144
	v_rcp_f32_e32 v145, v145
	v_rcp_f32_e32 v146, v146
	v_rcp_f32_e32 v147, v147
	v_pk_mul_f32 v[16:17], v[16:17], v[140:141]
	v_pk_mul_f32 v[18:19], v[18:19], v[142:143]
	v_pk_mul_f32 v[8:9], v[8:9], v[144:145]
	v_pk_mul_f32 v[10:11], v[10:11], v[146:147]
	v_pk_mul_f32 v[16:17], v[12:13], v[16:17]
	v_pk_mul_f32 v[18:19], v[14:15], v[18:19]
	v_pk_mul_f32 v[8:9], v[4:5], v[8:9]
	v_pk_mul_f32 v[10:11], v[6:7], v[10:11]
	v_cvt_pk_bf16_f32 v16, v16, v17
	v_cvt_pk_bf16_f32 v17, v18, v19
	v_cvt_pk_bf16_f32 v18, v8, v9
	v_cvt_pk_bf16_f32 v19, v10, v11
	s_mov_b32 s34, 0x2c000
	v_lshl_add_u64 v[138:139], v[136:137], 0, s[34:35]
	global_store_dwordx4 v[138:139], v[16:19], off
	s_mov_b64 s[34:35], -1
	s_and_b64 vcc, exec, s[38:39]
	s_cbranch_vccnz .LBB0_1305
	s_andn2_b64 vcc, exec, s[12:13]
	s_cbranch_vccnz .LBB0_1304
	s_barrier
	s_branch .LBB0_1304
